# nt only on last-use streaming accesses: residual loads of the P7/P10 epilogues and the loads+stores of the final norm P11
# speedup vs baseline: 1.0139x; 1.0139x over previous
.LBB0_893:
	s_cmp_gt_i32 s38, 32
	v_lshl_or_b32 v142, s12, 8, v165
	s_cselect_b32 s12, 0xc000, 0
	s_add_u32 s12, s30, s12
	v_ashrrev_i32_e32 v143, 31, v142
	s_addc_u32 s13, s31, 0
	v_lshlrev_b64 v[142:143], 2, v[142:143]
	v_lshl_add_u64 v[144:145], s[12:13], 0, v[142:143]
	v_lshl_add_u64 v[156:157], v[144:145], 0, s[10:11]
	v_add_co_u32_e32 v144, vcc, s59, v144
	v_lshl_add_u32 v171, s38, 8, v1
	s_nop 0
	v_addc_co_u32_e32 v145, vcc, 0, v145, vcc
	v_cmp_lt_i32_e32 vcc, s65, v171
	v_or_b32_e32 v177, 16, v171
	v_lshl_add_u64 v[158:159], s[6:7], 0, v[142:143]
	global_load_dwordx4 v[172:175], v[144:145], off nt
	global_load_dwordx4 v[178:181], v[158:159], off nt
	global_load_dwordx4 v[148:151], v[158:159], off offset:64 nt
	global_load_dwordx4 v[152:155], v[156:157], off offset:64 nt
	global_load_dwordx4 v[160:163], v[156:157], off offset:512 nt
	global_load_dwordx4 v[182:185], v[156:157], off offset:576 nt
	global_load_dwordx4 v[186:189], v[158:159], off offset:512 nt
	global_load_dwordx4 v[190:193], v[158:159], off offset:576 nt
	v_cndmask_b32_e32 v156, v169, v170, vcc
	v_cmp_lt_i32_e32 vcc, s65, v177
	v_add_u32_e32 v156, v156, v171
	v_ashrrev_i32_e32 v157, 31, v156
	v_cndmask_b32_e32 v206, v169, v170, vcc
	v_add_u32_e32 v206, v206, v177
	v_lshl_add_u64 v[144:145], s[36:37], 0, v[142:143]
	v_lshlrev_b64 v[156:157], 13, v[156:157]
	v_ashrrev_i32_e32 v207, 31, v206
	v_lshl_add_u64 v[158:159], v[144:145], 0, v[156:157]
	v_lshlrev_b64 v[226:227], 13, v[206:207]
	global_load_dwordx4 v[194:197], v[158:159], off offset:64 nt
	global_load_dwordx4 v[198:201], v[158:159], off offset:512 nt
	global_load_dwordx4 v[202:205], v[158:159], off offset:576 nt
	v_lshl_add_u64 v[222:223], v[144:145], 0, v[226:227]
	global_load_dwordx4 v[206:209], v[222:223], off offset:64 nt
	global_load_dwordx4 v[210:213], v[222:223], off offset:512 nt
	global_load_dwordx4 v[214:217], v[222:223], off offset:576 nt
	global_load_dwordx4 v[218:221], v[158:159], off nt
	s_nop 0
	global_load_dwordx4 v[222:225], v[222:223], off nt
	v_or_b32_e32 v158, 32, v171
	v_cmp_lt_i32_e32 vcc, s65, v158
	v_lshl_add_u64 v[156:157], s[28:29], 0, v[156:157]
	v_lshl_add_u64 v[230:231], v[156:157], 0, v[142:143]
	v_cndmask_b32_e32 v159, v169, v170, vcc
	v_add_u32_e32 v158, v159, v158
	v_ashrrev_i32_e32 v159, 31, v158
	v_lshl_add_u64 v[156:157], s[28:29], 0, v[226:227]
	v_lshlrev_b64 v[228:229], 13, v[158:159]
	v_lshl_add_u64 v[232:233], v[156:157], 0, v[142:143]
	v_lshl_add_u64 v[226:227], v[144:145], 0, v[228:229]
	s_waitcnt vmcnt(0)
	v_pk_add_f32 v[156:157], v[154:155], v[150:151]
	v_pk_add_f32 v[158:159], v[152:153], v[148:149]
	v_pk_add_f32 v[152:153], v[162:163], v[188:189]
	v_pk_add_f32 v[150:151], v[182:183], v[190:191]
	v_pk_add_f32 v[154:155], v[160:161], v[186:187]
	v_pk_add_f32 v[148:149], v[184:185], v[192:193]
	v_pk_add_f32 v[162:163], v[172:173], v[178:179]
	v_pk_add_f32 v[160:161], v[174:175], v[180:181]
	v_lshl_add_u64 v[180:181], s[28:29], 0, v[228:229]
	v_lshl_add_u64 v[180:181], v[180:181], 0, v[142:143]
	v_pk_fma_f32 v[128:129], v[128:129], v[156:157], v[196:197]
	v_pk_fma_f32 v[126:127], v[126:127], v[158:159], v[194:195]
	v_pk_fma_f32 v[106:107], v[106:107], v[150:151], v[202:203]
	v_pk_fma_f32 v[112:113], v[112:113], v[152:153], v[200:201]
	v_pk_fma_f32 v[110:111], v[110:111], v[154:155], v[198:199]
	v_pk_fma_f32 v[108:109], v[108:109], v[148:149], v[204:205]
	global_store_dwordx4 v[230:231], v[126:129], off offset:64
	global_store_dwordx4 v[230:231], v[110:113], off offset:512
	global_store_dwordx4 v[230:231], v[106:109], off offset:576
	v_pk_fma_f32 v[120:121], v[120:121], v[156:157], v[208:209]
	v_pk_fma_f32 v[118:119], v[118:119], v[158:159], v[206:207]
	v_pk_fma_f32 v[106:107], v[114:115], v[162:163], v[222:223]
	v_or_b32_e32 v114, 48, v171
	v_cmp_lt_i32_e32 vcc, s65, v114
	v_pk_fma_f32 v[104:105], v[104:105], v[152:153], v[212:213]
	v_pk_fma_f32 v[102:103], v[102:103], v[154:155], v[210:211]
	v_cndmask_b32_e32 v115, v169, v170, vcc
	v_add_u32_e32 v114, v115, v114
	v_ashrrev_i32_e32 v115, 31, v114
	v_pk_fma_f32 v[100:101], v[100:101], v[148:149], v[216:217]
	v_pk_fma_f32 v[98:99], v[98:99], v[150:151], v[214:215]
	v_pk_fma_f32 v[124:125], v[124:125], v[160:161], v[220:221]
	v_pk_fma_f32 v[122:123], v[122:123], v[162:163], v[218:219]
	v_pk_fma_f32 v[108:109], v[116:117], v[160:161], v[224:225]
	global_store_dwordx4 v[232:233], v[118:121], off offset:64
	global_store_dwordx4 v[232:233], v[102:105], off offset:512
	global_store_dwordx4 v[232:233], v[98:101], off offset:576
	global_store_dwordx4 v[230:231], v[122:125], off
	global_store_dwordx4 v[232:233], v[106:109], off
	v_lshlrev_b64 v[172:173], 13, v[114:115]
	v_lshl_add_u64 v[126:127], v[144:145], 0, v[172:173]
	global_load_dwordx4 v[98:101], v[226:227], off nt
	global_load_dwordx4 v[102:105], v[226:227], off offset:64 nt
	global_load_dwordx4 v[106:109], v[226:227], off offset:512 nt
	global_load_dwordx4 v[110:113], v[226:227], off offset:576 nt
	global_load_dwordx4 v[114:117], v[126:127], off nt
	global_load_dwordx4 v[118:121], v[126:127], off offset:64 nt
	global_load_dwordx4 v[122:125], v[126:127], off offset:512 nt
	s_nop 0
	global_load_dwordx4 v[126:129], v[126:127], off offset:576 nt
	v_cmp_lt_i32_e32 vcc, s66, v171
	v_lshl_add_u64 v[172:173], s[28:29], 0, v[172:173]
	v_lshl_add_u64 v[172:173], v[172:173], 0, v[142:143]
	v_cndmask_b32_e32 v174, v169, v170, vcc
	v_cmp_lt_i32_e32 vcc, s69, v171
	v_add3_u32 v174, v171, v174, s67
	v_ashrrev_i32_e32 v175, 31, v174
	v_cndmask_b32_e32 v177, v169, v170, vcc
	v_lshlrev_b64 v[174:175], 13, v[174:175]
	v_lshl_add_u64 v[178:179], v[144:145], 0, v[174:175]
	v_cmp_lt_i32_e32 vcc, s77, v171
	s_waitcnt vmcnt(7)
	v_pk_fma_f32 v[96:97], v[96:97], v[160:161], v[100:101]
	v_pk_fma_f32 v[94:95], v[94:95], v[162:163], v[98:99]
	s_waitcnt vmcnt(5)
	v_pk_fma_f32 v[78:79], v[78:79], v[154:155], v[106:107]
	v_pk_fma_f32 v[92:93], v[92:93], v[156:157], v[104:105]
	v_pk_fma_f32 v[90:91], v[90:91], v[158:159], v[102:103]
	v_pk_fma_f32 v[80:81], v[80:81], v[152:153], v[108:109]
	s_waitcnt vmcnt(4)
	v_pk_fma_f32 v[76:77], v[76:77], v[148:149], v[112:113]
	v_pk_fma_f32 v[74:75], v[74:75], v[150:151], v[110:111]
	s_waitcnt vmcnt(3)
	v_pk_fma_f32 v[88:89], v[88:89], v[160:161], v[116:117]
	v_pk_fma_f32 v[86:87], v[86:87], v[162:163], v[114:115]
	s_waitcnt vmcnt(2)
	v_pk_fma_f32 v[84:85], v[84:85], v[156:157], v[120:121]
	v_pk_fma_f32 v[82:83], v[82:83], v[158:159], v[118:119]
	s_waitcnt vmcnt(1)
	v_pk_fma_f32 v[72:73], v[72:73], v[152:153], v[124:125]
	v_pk_fma_f32 v[70:71], v[70:71], v[154:155], v[122:123]
	s_waitcnt vmcnt(0)
	v_pk_fma_f32 v[68:69], v[68:69], v[148:149], v[128:129]
	v_pk_fma_f32 v[66:67], v[66:67], v[150:151], v[126:127]
	global_store_dwordx4 v[180:181], v[94:97], off
	global_store_dwordx4 v[180:181], v[90:93], off offset:64
	global_store_dwordx4 v[180:181], v[78:81], off offset:512
	global_store_dwordx4 v[180:181], v[74:77], off offset:576
	global_store_dwordx4 v[172:173], v[86:89], off
	global_store_dwordx4 v[172:173], v[82:85], off offset:64
	global_store_dwordx4 v[172:173], v[70:73], off offset:512
	global_store_dwordx4 v[172:173], v[66:69], off offset:576
	v_add3_u32 v78, v171, v177, s76
	v_ashrrev_i32_e32 v79, 31, v78
	v_lshlrev_b64 v[98:99], 13, v[78:79]
	global_load_dwordx4 v[66:69], v[178:179], off nt
	global_load_dwordx4 v[70:73], v[178:179], off offset:64 nt
	global_load_dwordx4 v[74:77], v[178:179], off offset:512 nt
	global_load_dwordx4 v[78:81], v[178:179], off offset:576 nt
	v_lshl_add_u64 v[94:95], v[144:145], 0, v[98:99]
	global_load_dwordx4 v[82:85], v[94:95], off nt
	global_load_dwordx4 v[86:89], v[94:95], off offset:64 nt
	global_load_dwordx4 v[90:93], v[94:95], off offset:512 nt
	s_nop 0
	global_load_dwordx4 v[94:97], v[94:95], off offset:576 nt
	v_cndmask_b32_e32 v100, v169, v170, vcc
	v_cmp_lt_i32_e32 vcc, s79, v171
	v_lshl_add_u64 v[102:103], s[28:29], 0, v[174:175]
	v_add3_u32 v100, v171, v100, s78
	v_cndmask_b32_e32 v106, v169, v170, vcc
	v_lshl_add_u64 v[98:99], s[28:29], 0, v[98:99]
	v_lshl_add_u64 v[102:103], v[102:103], 0, v[142:143]
	v_ashrrev_i32_e32 v101, 31, v100
	v_lshl_add_u64 v[98:99], v[98:99], 0, v[142:143]
	v_lshlrev_b64 v[100:101], 13, v[100:101]
	v_lshl_add_u64 v[104:105], v[144:145], 0, v[100:101]
	s_andn2_b64 vcc, exec, s[2:3]
	s_mov_b64 s[2:3], -1
	s_waitcnt vmcnt(7)
	v_pk_fma_f32 v[64:65], v[64:65], v[160:161], v[68:69]
	v_pk_fma_f32 v[62:63], v[62:63], v[162:163], v[66:67]
	s_waitcnt vmcnt(5)
	v_pk_fma_f32 v[46:47], v[46:47], v[154:155], v[74:75]
	v_pk_fma_f32 v[60:61], v[60:61], v[156:157], v[72:73]
	v_pk_fma_f32 v[58:59], v[58:59], v[158:159], v[70:71]
	v_pk_fma_f32 v[48:49], v[48:49], v[152:153], v[76:77]
	s_waitcnt vmcnt(4)
	v_pk_fma_f32 v[44:45], v[44:45], v[148:149], v[80:81]
	v_pk_fma_f32 v[42:43], v[42:43], v[150:151], v[78:79]
	s_waitcnt vmcnt(3)
	v_pk_fma_f32 v[56:57], v[56:57], v[160:161], v[84:85]
	v_pk_fma_f32 v[54:55], v[54:55], v[162:163], v[82:83]
	s_waitcnt vmcnt(2)
	v_pk_fma_f32 v[52:53], v[52:53], v[156:157], v[88:89]
	v_pk_fma_f32 v[50:51], v[50:51], v[158:159], v[86:87]
	s_waitcnt vmcnt(1)
	v_pk_fma_f32 v[40:41], v[40:41], v[152:153], v[92:93]
	v_pk_fma_f32 v[38:39], v[38:39], v[154:155], v[90:91]
	s_waitcnt vmcnt(0)
	v_pk_fma_f32 v[36:37], v[36:37], v[148:149], v[96:97]
	v_pk_fma_f32 v[34:35], v[34:35], v[150:151], v[94:95]
	global_store_dwordx4 v[102:103], v[62:65], off
	global_store_dwordx4 v[102:103], v[58:61], off offset:64
	global_store_dwordx4 v[102:103], v[46:49], off offset:512
	global_store_dwordx4 v[102:103], v[42:45], off offset:576
	global_store_dwordx4 v[98:99], v[54:57], off
	global_store_dwordx4 v[98:99], v[50:53], off offset:64
	global_store_dwordx4 v[98:99], v[38:41], off offset:512
	global_store_dwordx4 v[98:99], v[34:37], off offset:576
	v_add3_u32 v46, v171, v106, s80
	v_ashrrev_i32_e32 v47, 31, v46
	v_lshlrev_b64 v[66:67], 13, v[46:47]
	global_load_dwordx4 v[34:37], v[104:105], off nt
	global_load_dwordx4 v[38:41], v[104:105], off offset:64 nt
	v_lshl_add_u64 v[62:63], v[144:145], 0, v[66:67]
	global_load_dwordx4 v[42:45], v[104:105], off offset:512 nt
	global_load_dwordx4 v[46:49], v[104:105], off offset:576 nt
	global_load_dwordx4 v[50:53], v[62:63], off nt
	global_load_dwordx4 v[54:57], v[62:63], off offset:64 nt
	global_load_dwordx4 v[58:61], v[62:63], off offset:512 nt
	s_nop 0
	global_load_dwordx4 v[62:65], v[62:63], off offset:576 nt
	v_lshl_add_u64 v[68:69], s[28:29], 0, v[100:101]
	v_lshl_add_u64 v[66:67], s[28:29], 0, v[66:67]
	v_lshl_add_u64 v[68:69], v[68:69], 0, v[142:143]
	v_lshl_add_u64 v[66:67], v[66:67], 0, v[142:143]
	s_waitcnt vmcnt(7)
	v_pk_fma_f32 v[32:33], v[32:33], v[160:161], v[36:37]
	v_pk_fma_f32 v[30:31], v[30:31], v[162:163], v[34:35]
	s_waitcnt vmcnt(6)
	v_pk_fma_f32 v[28:29], v[28:29], v[156:157], v[40:41]
	v_pk_fma_f32 v[26:27], v[26:27], v[158:159], v[38:39]
	s_waitcnt vmcnt(5)
	v_pk_fma_f32 v[16:17], v[16:17], v[152:153], v[44:45]
	v_pk_fma_f32 v[14:15], v[14:15], v[154:155], v[42:43]
	s_waitcnt vmcnt(4)
	v_pk_fma_f32 v[12:13], v[12:13], v[148:149], v[48:49]
	v_pk_fma_f32 v[10:11], v[10:11], v[150:151], v[46:47]
	s_waitcnt vmcnt(3)
	v_pk_fma_f32 v[24:25], v[24:25], v[160:161], v[52:53]
	v_pk_fma_f32 v[22:23], v[22:23], v[162:163], v[50:51]
	s_waitcnt vmcnt(2)
	v_pk_fma_f32 v[20:21], v[20:21], v[156:157], v[56:57]
	v_pk_fma_f32 v[18:19], v[18:19], v[158:159], v[54:55]
	s_waitcnt vmcnt(1)
	v_pk_fma_f32 v[8:9], v[8:9], v[152:153], v[60:61]
	v_pk_fma_f32 v[6:7], v[6:7], v[154:155], v[58:59]
	s_waitcnt vmcnt(0)
	v_pk_fma_f32 v[4:5], v[4:5], v[148:149], v[64:65]
	v_pk_fma_f32 v[2:3], v[2:3], v[150:151], v[62:63]
	global_store_dwordx4 v[68:69], v[30:33], off
	global_store_dwordx4 v[68:69], v[26:29], off offset:64
	global_store_dwordx4 v[68:69], v[14:17], off offset:512
	global_store_dwordx4 v[68:69], v[10:13], off offset:576
	global_store_dwordx4 v[66:67], v[22:25], off
	global_store_dwordx4 v[66:67], v[18:21], off offset:64
	global_store_dwordx4 v[66:67], v[6:9], off offset:512
	global_store_dwordx4 v[66:67], v[2:5], off offset:576
	s_cbranch_vccnz .LBB0_882
	s_andn2_b64 vcc, exec, s[4:5]
	s_cbranch_vccnz .LBB0_881
	s_barrier
	s_branch .LBB0_881

.LBB0_1141:
	s_cmp_gt_i32 s12, 32
	v_lshl_or_b32 v142, s13, 8, v165
	s_cselect_b32 s13, 0xc000, 0
	s_add_u32 s22, s30, s13
	v_ashrrev_i32_e32 v143, 31, v142
	s_addc_u32 s23, s31, 0
	v_lshlrev_b64 v[142:143], 2, v[142:143]
	v_lshl_add_u64 v[144:145], s[22:23], 0, v[142:143]
	v_lshl_add_u64 v[156:157], v[144:145], 0, s[16:17]
	v_add_co_u32_e32 v144, vcc, s54, v144
	v_lshl_add_u32 v171, s12, 8, v1
	s_nop 0
	v_addc_co_u32_e32 v145, vcc, 0, v145, vcc
	v_cmp_lt_i32_e32 vcc, s56, v171
	v_or_b32_e32 v177, 16, v171
	v_lshl_add_u64 v[158:159], s[18:19], 0, v[142:143]
	global_load_dwordx4 v[172:175], v[144:145], off nt
	global_load_dwordx4 v[178:181], v[158:159], off nt
	global_load_dwordx4 v[148:151], v[158:159], off offset:64 nt
	global_load_dwordx4 v[152:155], v[156:157], off offset:64 nt
	global_load_dwordx4 v[160:163], v[156:157], off offset:512 nt
	global_load_dwordx4 v[182:185], v[156:157], off offset:576 nt
	global_load_dwordx4 v[186:189], v[158:159], off offset:512 nt
	global_load_dwordx4 v[190:193], v[158:159], off offset:576 nt
	v_cndmask_b32_e32 v156, v169, v170, vcc
	v_cmp_lt_i32_e32 vcc, s56, v177
	v_add_u32_e32 v156, v156, v171
	v_ashrrev_i32_e32 v157, 31, v156
	v_cndmask_b32_e32 v206, v169, v170, vcc
	v_add_u32_e32 v206, v206, v177
	v_lshl_add_u64 v[144:145], s[28:29], 0, v[142:143]
	v_lshlrev_b64 v[156:157], 13, v[156:157]
	v_ashrrev_i32_e32 v207, 31, v206
	v_lshl_add_u64 v[158:159], v[144:145], 0, v[156:157]
	v_lshlrev_b64 v[226:227], 13, v[206:207]
	global_load_dwordx4 v[194:197], v[158:159], off offset:64 nt
	global_load_dwordx4 v[198:201], v[158:159], off offset:512 nt
	global_load_dwordx4 v[202:205], v[158:159], off offset:576 nt
	v_lshl_add_u64 v[222:223], v[144:145], 0, v[226:227]
	global_load_dwordx4 v[206:209], v[222:223], off offset:64 nt
	global_load_dwordx4 v[210:213], v[222:223], off offset:512 nt
	global_load_dwordx4 v[214:217], v[222:223], off offset:576 nt
	global_load_dwordx4 v[218:221], v[158:159], off nt
	s_nop 0
	global_load_dwordx4 v[222:225], v[222:223], off nt
	v_or_b32_e32 v158, 32, v171
	v_cmp_lt_i32_e32 vcc, s56, v158
	v_lshl_add_u64 v[156:157], s[28:29], 0, v[156:157]
	v_lshl_add_u64 v[230:231], v[156:157], 0, v[142:143]
	v_cndmask_b32_e32 v159, v169, v170, vcc
	v_add_u32_e32 v158, v159, v158
	v_ashrrev_i32_e32 v159, 31, v158
	v_lshl_add_u64 v[156:157], s[28:29], 0, v[226:227]
	v_lshlrev_b64 v[228:229], 13, v[158:159]
	v_lshl_add_u64 v[232:233], v[156:157], 0, v[142:143]
	v_lshl_add_u64 v[226:227], v[144:145], 0, v[228:229]
	s_waitcnt vmcnt(0)
	v_pk_add_f32 v[156:157], v[154:155], v[150:151]
	v_pk_add_f32 v[158:159], v[152:153], v[148:149]
	v_pk_add_f32 v[152:153], v[162:163], v[188:189]
	v_pk_add_f32 v[150:151], v[182:183], v[190:191]
	v_pk_add_f32 v[154:155], v[160:161], v[186:187]
	v_pk_add_f32 v[148:149], v[184:185], v[192:193]
	v_pk_add_f32 v[162:163], v[172:173], v[178:179]
	v_pk_add_f32 v[160:161], v[174:175], v[180:181]
	v_lshl_add_u64 v[180:181], s[28:29], 0, v[228:229]
	v_lshl_add_u64 v[180:181], v[180:181], 0, v[142:143]
	v_pk_fma_f32 v[128:129], v[128:129], v[156:157], v[196:197]
	v_pk_fma_f32 v[126:127], v[126:127], v[158:159], v[194:195]
	v_pk_fma_f32 v[106:107], v[106:107], v[150:151], v[202:203]
	v_pk_fma_f32 v[112:113], v[112:113], v[152:153], v[200:201]
	v_pk_fma_f32 v[110:111], v[110:111], v[154:155], v[198:199]
	v_pk_fma_f32 v[108:109], v[108:109], v[148:149], v[204:205]
	global_store_dwordx4 v[230:231], v[126:129], off offset:64
	global_store_dwordx4 v[230:231], v[110:113], off offset:512
	global_store_dwordx4 v[230:231], v[106:109], off offset:576
	v_pk_fma_f32 v[120:121], v[120:121], v[156:157], v[208:209]
	v_pk_fma_f32 v[118:119], v[118:119], v[158:159], v[206:207]
	v_pk_fma_f32 v[106:107], v[114:115], v[162:163], v[222:223]
	v_or_b32_e32 v114, 48, v171
	v_cmp_lt_i32_e32 vcc, s56, v114
	v_pk_fma_f32 v[104:105], v[104:105], v[152:153], v[212:213]
	v_pk_fma_f32 v[102:103], v[102:103], v[154:155], v[210:211]
	v_cndmask_b32_e32 v115, v169, v170, vcc
	v_add_u32_e32 v114, v115, v114
	v_ashrrev_i32_e32 v115, 31, v114
	v_pk_fma_f32 v[100:101], v[100:101], v[148:149], v[216:217]
	v_pk_fma_f32 v[98:99], v[98:99], v[150:151], v[214:215]
	v_pk_fma_f32 v[124:125], v[124:125], v[160:161], v[220:221]
	v_pk_fma_f32 v[122:123], v[122:123], v[162:163], v[218:219]
	v_pk_fma_f32 v[108:109], v[116:117], v[160:161], v[224:225]
	global_store_dwordx4 v[232:233], v[118:121], off offset:64
	global_store_dwordx4 v[232:233], v[102:105], off offset:512
	global_store_dwordx4 v[232:233], v[98:101], off offset:576
	global_store_dwordx4 v[230:231], v[122:125], off
	global_store_dwordx4 v[232:233], v[106:109], off
	v_lshlrev_b64 v[172:173], 13, v[114:115]
	v_lshl_add_u64 v[126:127], v[144:145], 0, v[172:173]
	global_load_dwordx4 v[98:101], v[226:227], off nt
	global_load_dwordx4 v[102:105], v[226:227], off offset:64 nt
	global_load_dwordx4 v[106:109], v[226:227], off offset:512 nt
	global_load_dwordx4 v[110:113], v[226:227], off offset:576 nt
	global_load_dwordx4 v[114:117], v[126:127], off nt
	global_load_dwordx4 v[118:121], v[126:127], off offset:64 nt
	global_load_dwordx4 v[122:125], v[126:127], off offset:512 nt
	s_nop 0
	global_load_dwordx4 v[126:129], v[126:127], off offset:576 nt
	v_cmp_lt_i32_e32 vcc, s57, v171
	v_lshl_add_u64 v[172:173], s[28:29], 0, v[172:173]
	v_lshl_add_u64 v[172:173], v[172:173], 0, v[142:143]
	v_cndmask_b32_e32 v174, v169, v170, vcc
	v_cmp_lt_i32_e32 vcc, s59, v171
	v_add3_u32 v174, v171, v174, s58
	v_ashrrev_i32_e32 v175, 31, v174
	v_cndmask_b32_e32 v177, v169, v170, vcc
	v_lshlrev_b64 v[174:175], 13, v[174:175]
	v_lshl_add_u64 v[178:179], v[144:145], 0, v[174:175]
	v_cmp_lt_i32_e32 vcc, s61, v171
	s_waitcnt vmcnt(7)
	v_pk_fma_f32 v[96:97], v[96:97], v[160:161], v[100:101]
	v_pk_fma_f32 v[94:95], v[94:95], v[162:163], v[98:99]
	s_waitcnt vmcnt(5)
	v_pk_fma_f32 v[78:79], v[78:79], v[154:155], v[106:107]
	v_pk_fma_f32 v[92:93], v[92:93], v[156:157], v[104:105]
	v_pk_fma_f32 v[90:91], v[90:91], v[158:159], v[102:103]
	v_pk_fma_f32 v[80:81], v[80:81], v[152:153], v[108:109]
	s_waitcnt vmcnt(4)
	v_pk_fma_f32 v[76:77], v[76:77], v[148:149], v[112:113]
	v_pk_fma_f32 v[74:75], v[74:75], v[150:151], v[110:111]
	s_waitcnt vmcnt(3)
	v_pk_fma_f32 v[88:89], v[88:89], v[160:161], v[116:117]
	v_pk_fma_f32 v[86:87], v[86:87], v[162:163], v[114:115]
	s_waitcnt vmcnt(2)
	v_pk_fma_f32 v[84:85], v[84:85], v[156:157], v[120:121]
	v_pk_fma_f32 v[82:83], v[82:83], v[158:159], v[118:119]
	s_waitcnt vmcnt(1)
	v_pk_fma_f32 v[72:73], v[72:73], v[152:153], v[124:125]
	v_pk_fma_f32 v[70:71], v[70:71], v[154:155], v[122:123]
	s_waitcnt vmcnt(0)
	v_pk_fma_f32 v[68:69], v[68:69], v[148:149], v[128:129]
	v_pk_fma_f32 v[66:67], v[66:67], v[150:151], v[126:127]
	global_store_dwordx4 v[180:181], v[94:97], off
	global_store_dwordx4 v[180:181], v[90:93], off offset:64
	global_store_dwordx4 v[180:181], v[78:81], off offset:512
	global_store_dwordx4 v[180:181], v[74:77], off offset:576
	global_store_dwordx4 v[172:173], v[86:89], off
	global_store_dwordx4 v[172:173], v[82:85], off offset:64
	global_store_dwordx4 v[172:173], v[70:73], off offset:512
	global_store_dwordx4 v[172:173], v[66:69], off offset:576
	v_add3_u32 v78, v171, v177, s60
	v_ashrrev_i32_e32 v79, 31, v78
	v_lshlrev_b64 v[98:99], 13, v[78:79]
	global_load_dwordx4 v[66:69], v[178:179], off nt
	global_load_dwordx4 v[70:73], v[178:179], off offset:64 nt
	global_load_dwordx4 v[74:77], v[178:179], off offset:512 nt
	global_load_dwordx4 v[78:81], v[178:179], off offset:576 nt
	v_lshl_add_u64 v[94:95], v[144:145], 0, v[98:99]
	global_load_dwordx4 v[82:85], v[94:95], off nt
	global_load_dwordx4 v[86:89], v[94:95], off offset:64 nt
	global_load_dwordx4 v[90:93], v[94:95], off offset:512 nt
	s_nop 0
	global_load_dwordx4 v[94:97], v[94:95], off offset:576 nt
	v_cndmask_b32_e32 v100, v169, v170, vcc
	v_cmp_lt_i32_e32 vcc, s63, v171
	v_lshl_add_u64 v[102:103], s[28:29], 0, v[174:175]
	v_add3_u32 v100, v171, v100, s62
	v_cndmask_b32_e32 v106, v169, v170, vcc
	v_lshl_add_u64 v[98:99], s[28:29], 0, v[98:99]
	v_lshl_add_u64 v[102:103], v[102:103], 0, v[142:143]
	v_ashrrev_i32_e32 v101, 31, v100
	v_lshl_add_u64 v[98:99], v[98:99], 0, v[142:143]
	v_lshlrev_b64 v[100:101], 13, v[100:101]
	v_lshl_add_u64 v[104:105], v[144:145], 0, v[100:101]
	s_and_b64 vcc, exec, s[2:3]
	s_mov_b64 s[2:3], -1
	s_waitcnt vmcnt(7)
	v_pk_fma_f32 v[64:65], v[64:65], v[160:161], v[68:69]
	v_pk_fma_f32 v[62:63], v[62:63], v[162:163], v[66:67]
	s_waitcnt vmcnt(5)
	v_pk_fma_f32 v[46:47], v[46:47], v[154:155], v[74:75]
	v_pk_fma_f32 v[60:61], v[60:61], v[156:157], v[72:73]
	v_pk_fma_f32 v[58:59], v[58:59], v[158:159], v[70:71]
	v_pk_fma_f32 v[48:49], v[48:49], v[152:153], v[76:77]
	s_waitcnt vmcnt(4)
	v_pk_fma_f32 v[44:45], v[44:45], v[148:149], v[80:81]
	v_pk_fma_f32 v[42:43], v[42:43], v[150:151], v[78:79]
	s_waitcnt vmcnt(3)
	v_pk_fma_f32 v[56:57], v[56:57], v[160:161], v[84:85]
	v_pk_fma_f32 v[54:55], v[54:55], v[162:163], v[82:83]
	s_waitcnt vmcnt(2)
	v_pk_fma_f32 v[52:53], v[52:53], v[156:157], v[88:89]
	v_pk_fma_f32 v[50:51], v[50:51], v[158:159], v[86:87]
	s_waitcnt vmcnt(1)
	v_pk_fma_f32 v[40:41], v[40:41], v[152:153], v[92:93]
	v_pk_fma_f32 v[38:39], v[38:39], v[154:155], v[90:91]
	s_waitcnt vmcnt(0)
	v_pk_fma_f32 v[36:37], v[36:37], v[148:149], v[96:97]
	v_pk_fma_f32 v[34:35], v[34:35], v[150:151], v[94:95]
	global_store_dwordx4 v[102:103], v[62:65], off
	global_store_dwordx4 v[102:103], v[58:61], off offset:64
	global_store_dwordx4 v[102:103], v[46:49], off offset:512
	global_store_dwordx4 v[102:103], v[42:45], off offset:576
	global_store_dwordx4 v[98:99], v[54:57], off
	global_store_dwordx4 v[98:99], v[50:53], off offset:64
	global_store_dwordx4 v[98:99], v[38:41], off offset:512
	global_store_dwordx4 v[98:99], v[34:37], off offset:576
	v_add3_u32 v46, v171, v106, s64
	v_ashrrev_i32_e32 v47, 31, v46
	v_lshlrev_b64 v[66:67], 13, v[46:47]
	global_load_dwordx4 v[34:37], v[104:105], off nt
	global_load_dwordx4 v[38:41], v[104:105], off offset:64 nt
	v_lshl_add_u64 v[62:63], v[144:145], 0, v[66:67]
	global_load_dwordx4 v[42:45], v[104:105], off offset:512 nt
	global_load_dwordx4 v[46:49], v[104:105], off offset:576 nt
	global_load_dwordx4 v[50:53], v[62:63], off nt
	global_load_dwordx4 v[54:57], v[62:63], off offset:64 nt
	global_load_dwordx4 v[58:61], v[62:63], off offset:512 nt
	s_nop 0
	global_load_dwordx4 v[62:65], v[62:63], off offset:576 nt
	v_lshl_add_u64 v[68:69], s[28:29], 0, v[100:101]
	v_lshl_add_u64 v[66:67], s[28:29], 0, v[66:67]
	v_lshl_add_u64 v[68:69], v[68:69], 0, v[142:143]
	v_lshl_add_u64 v[66:67], v[66:67], 0, v[142:143]
	s_waitcnt vmcnt(7)
	v_pk_fma_f32 v[32:33], v[32:33], v[160:161], v[36:37]
	v_pk_fma_f32 v[30:31], v[30:31], v[162:163], v[34:35]
	s_waitcnt vmcnt(6)
	v_pk_fma_f32 v[28:29], v[28:29], v[156:157], v[40:41]
	v_pk_fma_f32 v[26:27], v[26:27], v[158:159], v[38:39]
	s_waitcnt vmcnt(5)
	v_pk_fma_f32 v[16:17], v[16:17], v[152:153], v[44:45]
	v_pk_fma_f32 v[14:15], v[14:15], v[154:155], v[42:43]
	s_waitcnt vmcnt(4)
	v_pk_fma_f32 v[12:13], v[12:13], v[148:149], v[48:49]
	v_pk_fma_f32 v[10:11], v[10:11], v[150:151], v[46:47]
	s_waitcnt vmcnt(3)
	v_pk_fma_f32 v[24:25], v[24:25], v[160:161], v[52:53]
	v_pk_fma_f32 v[22:23], v[22:23], v[162:163], v[50:51]
	s_waitcnt vmcnt(2)
	v_pk_fma_f32 v[20:21], v[20:21], v[156:157], v[56:57]
	v_pk_fma_f32 v[18:19], v[18:19], v[158:159], v[54:55]
	s_waitcnt vmcnt(1)
	v_pk_fma_f32 v[8:9], v[8:9], v[152:153], v[60:61]
	v_pk_fma_f32 v[6:7], v[6:7], v[154:155], v[58:59]
	s_waitcnt vmcnt(0)
	v_pk_fma_f32 v[4:5], v[4:5], v[148:149], v[64:65]
	v_pk_fma_f32 v[2:3], v[2:3], v[150:151], v[62:63]
	global_store_dwordx4 v[68:69], v[30:33], off
	global_store_dwordx4 v[68:69], v[26:29], off offset:64
	global_store_dwordx4 v[68:69], v[14:17], off offset:512
	global_store_dwordx4 v[68:69], v[10:13], off offset:576
	global_store_dwordx4 v[66:67], v[22:25], off
	global_store_dwordx4 v[66:67], v[18:21], off offset:64
	global_store_dwordx4 v[66:67], v[6:9], off offset:512
	global_store_dwordx4 v[66:67], v[2:5], off offset:576
	s_cbranch_vccnz .LBB0_1126
	s_andn2_b64 vcc, exec, s[6:7]
	s_cbranch_vccnz .LBB0_1125
	s_barrier
	s_branch .LBB0_1125
